# attention: static s_setprio 1 for the older wave half (waves 0-3) during the attention phase (on top of v36)
# baseline (speedup 1.0000x reference)
; #define LAUNDER() int tid, blk = blk0, G = G0; asm volatile("v_mbcnt_lo_u32_b32 %0, -1, 0\n\tv_mbcnt_hi_u32_b32 %0, -1, %0" : "=v"(tid)); tid += wave_s * 64; asm volatile("" : "+v"(tid), "+s"(blk), "+s"(G))
; #define GRID_BAR() do { xcd_barrier(xbar); } while (0)
; __device__ __forceinline__ void attn_phase(unsigned char* lds, const Params& p, int jl, const bf16_t* proj, bf16_t* mix, int blk, int G, int tid) {
;     ...
;     for (int gi = blk * 512 + tid; gi < 2560 * 2 * 256; gi += G * 512) {
;         const int c8 = gi & 255, kv = (gi >> 8) & 1, r = gi >> 9;
;         size_t srow, dst;
;         if (r < 2048) { const int b = r >> 9, tp = r & 511; srow = (size_t)b * 8192 + 7680 + tp; dst = (kv ? O_CVP : O_CKP) + ((size_t)(jl * 4 + b) * 512 + tp) * DM + c8 * 8; }
;         else { const int rs = r - 2048; srow = (size_t)MPR + rs; dst = (kv ? O_CVS : O_CKS) + ((size_t)jl * 512 + rs) * DM + c8 * 8; }
;         const bf16x8 x = *(const bf16x8*)(proj + srow * N4 + 2048 + kv * 2048 + c8 * 8);
; __global__ void __launch_bounds__(512, 2) fwd_kernel(Params p) {
;     ...
;         if ((layer & 1) == 0) { { LAUNDER(); hgrn_a(lds, p, jl, proj, mix, dbuf, scr, useg, dseg, blk, G, tid); } GRID_BAR(); { LAUNDER(); hgrn_b(lds, p, jl, proj, mix, dbuf, scr, useg, dseg, blk, G, tid); } }
;         else { LAUNDER(); attn_phase(lds, p, jl, proj, mix, blk, G, tid); }
.LBB0_122:
	s_or_b64 exec, exec, s[2:3]
	v_readlane_b32 s2, v255, 24
	v_readlane_b32 s3, v255, 25
	s_lshr_b32 s3, s2, 1
	s_bitcmp1_b32 s2, 0
	s_cselect_b64 s[4:5], -1, 0
	v_writelane_b32 v255, s3, 26
	s_mov_b64 s[2:3], -1
	s_and_b64 vcc, exec, s[4:5]
	s_waitcnt lgkmcnt(0)
	s_barrier
	s_cbranch_vccz .LBB0_223
	s_cmp_ge_u32 s62, 0x100
	s_cbranch_scc1 .Lattn_prio_skip
	s_setprio 1
